# w_idx side product: rolling window of 16 A/B fragment pairs in flight instead of load-pair/wait(0)/mfma 64 times; the 4 rows' ssq partial loads in one batch
# baseline (speedup 1.0000x reference)
;     ...
;                 for (int grp = bx * 8 + wave; grp < TOK / 16; grp += G * 8) {
;                     const bf16* pa = HB + (size_t)(grp * 16 + (lane & 15)) * DM + 8 * (lane >> 4);
;                     const bf16* pb = W8T + ((size_t)L * 16 + (lane & 15)) * DM + 8 * (lane >> 4);
;                     f32x4 acc = (f32x4){0.f, 0.f, 0.f, 0.f};
; #pragma unroll 16
;                     for (int s = 0; s < DM / 32; ++s) acc = __builtin_amdgcn_mfma_f32_16x16x32_bf16(*(const att::bf16x8*)(pa + 32 * s), *(const att::bf16x8*)(pb + 32 * s), acc, 0, 0, 0);
.LBB0_526:
	v_add_co_u32_e32 v16, vcc, 0xe510000, v14
	s_nop 1
	v_addc_co_u32_e32 v17, vcc, 0, v15, vcc
	global_load_dwordx4 v[40:43], v[16:17], off
	global_load_dwordx4 v[44:47], v[12:13], off offset:-512
	global_load_dwordx4 v[48:51], v[16:17], off offset:64
	global_load_dwordx4 v[52:55], v[12:13], off offset:-448
	global_load_dwordx4 v[56:59], v[16:17], off offset:128
	global_load_dwordx4 v[60:63], v[12:13], off offset:-384
	global_load_dwordx4 v[64:67], v[16:17], off offset:192
	global_load_dwordx4 v[68:71], v[12:13], off offset:-320
	global_load_dwordx4 v[72:75], v[16:17], off offset:256
	global_load_dwordx4 v[76:79], v[12:13], off offset:-256
	global_load_dwordx4 v[80:83], v[16:17], off offset:320
	global_load_dwordx4 v[84:87], v[12:13], off offset:-192
	global_load_dwordx4 v[88:91], v[16:17], off offset:384
	global_load_dwordx4 v[92:95], v[12:13], off offset:-128
	global_load_dwordx4 v[96:99], v[16:17], off offset:448
	global_load_dwordx4 v[100:103], v[12:13], off offset:-64
	global_load_dwordx4 v[104:107], v[16:17], off offset:512
	global_load_dwordx4 v[108:111], v[12:13], off
	global_load_dwordx4 v[112:115], v[16:17], off offset:576
	global_load_dwordx4 v[116:119], v[12:13], off offset:64
	global_load_dwordx4 v[120:123], v[16:17], off offset:640
	global_load_dwordx4 v[124:127], v[12:13], off offset:128
	global_load_dwordx4 v[128:131], v[16:17], off offset:704
	global_load_dwordx4 v[132:135], v[12:13], off offset:192
	global_load_dwordx4 v[136:139], v[16:17], off offset:768
	global_load_dwordx4 v[140:143], v[12:13], off offset:256
	global_load_dwordx4 v[144:147], v[16:17], off offset:832
	global_load_dwordx4 v[148:151], v[12:13], off offset:320
	global_load_dwordx4 v[152:155], v[16:17], off offset:896
	global_load_dwordx4 v[156:159], v[12:13], off offset:384
	global_load_dwordx4 v[160:163], v[16:17], off offset:960
	global_load_dwordx4 v[164:167], v[12:13], off offset:448
	s_waitcnt vmcnt(30)
	v_mfma_f32_16x16x32_bf16 v[2:5], v[40:43], v[44:47], v[2:5]
	global_load_dwordx4 v[40:43], v[16:17], off offset:1024
	global_load_dwordx4 v[44:47], v[12:13], off offset:512
	s_waitcnt vmcnt(30)
	v_mfma_f32_16x16x32_bf16 v[2:5], v[48:51], v[52:55], v[2:5]
	global_load_dwordx4 v[48:51], v[16:17], off offset:1088
	global_load_dwordx4 v[52:55], v[12:13], off offset:576
	s_waitcnt vmcnt(30)
	v_mfma_f32_16x16x32_bf16 v[2:5], v[56:59], v[60:63], v[2:5]
	global_load_dwordx4 v[56:59], v[16:17], off offset:1152
	global_load_dwordx4 v[60:63], v[12:13], off offset:640
	s_waitcnt vmcnt(30)
	v_mfma_f32_16x16x32_bf16 v[2:5], v[64:67], v[68:71], v[2:5]
	global_load_dwordx4 v[64:67], v[16:17], off offset:1216
	global_load_dwordx4 v[68:71], v[12:13], off offset:704
	s_waitcnt vmcnt(30)
	v_mfma_f32_16x16x32_bf16 v[2:5], v[72:75], v[76:79], v[2:5]
	global_load_dwordx4 v[72:75], v[16:17], off offset:1280
	global_load_dwordx4 v[76:79], v[12:13], off offset:768
	s_waitcnt vmcnt(30)
	v_mfma_f32_16x16x32_bf16 v[2:5], v[80:83], v[84:87], v[2:5]
	global_load_dwordx4 v[80:83], v[16:17], off offset:1344
	global_load_dwordx4 v[84:87], v[12:13], off offset:832
	s_waitcnt vmcnt(30)
	v_mfma_f32_16x16x32_bf16 v[2:5], v[88:91], v[92:95], v[2:5]
	global_load_dwordx4 v[88:91], v[16:17], off offset:1408
	global_load_dwordx4 v[92:95], v[12:13], off offset:896
	s_waitcnt vmcnt(30)
	v_mfma_f32_16x16x32_bf16 v[2:5], v[96:99], v[100:103], v[2:5]
	global_load_dwordx4 v[96:99], v[16:17], off offset:1472
	global_load_dwordx4 v[100:103], v[12:13], off offset:960
	s_waitcnt vmcnt(30)
	v_mfma_f32_16x16x32_bf16 v[2:5], v[104:107], v[108:111], v[2:5]
	global_load_dwordx4 v[104:107], v[16:17], off offset:1536
	global_load_dwordx4 v[108:111], v[12:13], off offset:1024
	s_waitcnt vmcnt(30)
	v_mfma_f32_16x16x32_bf16 v[2:5], v[112:115], v[116:119], v[2:5]
	global_load_dwordx4 v[112:115], v[16:17], off offset:1600
	global_load_dwordx4 v[116:119], v[12:13], off offset:1088
	s_waitcnt vmcnt(30)
	v_mfma_f32_16x16x32_bf16 v[2:5], v[120:123], v[124:127], v[2:5]
	global_load_dwordx4 v[120:123], v[16:17], off offset:1664
	global_load_dwordx4 v[124:127], v[12:13], off offset:1152
	s_waitcnt vmcnt(30)
	v_mfma_f32_16x16x32_bf16 v[2:5], v[128:131], v[132:135], v[2:5]
	global_load_dwordx4 v[128:131], v[16:17], off offset:1728
	global_load_dwordx4 v[132:135], v[12:13], off offset:1216
	s_waitcnt vmcnt(30)
	v_mfma_f32_16x16x32_bf16 v[2:5], v[136:139], v[140:143], v[2:5]
	global_load_dwordx4 v[136:139], v[16:17], off offset:1792
	global_load_dwordx4 v[140:143], v[12:13], off offset:1280
	s_waitcnt vmcnt(30)
	v_mfma_f32_16x16x32_bf16 v[2:5], v[144:147], v[148:151], v[2:5]
	global_load_dwordx4 v[144:147], v[16:17], off offset:1856
	global_load_dwordx4 v[148:151], v[12:13], off offset:1344
	s_waitcnt vmcnt(30)
	v_mfma_f32_16x16x32_bf16 v[2:5], v[152:155], v[156:159], v[2:5]
	global_load_dwordx4 v[152:155], v[16:17], off offset:1920
	global_load_dwordx4 v[156:159], v[12:13], off offset:1408
	s_waitcnt vmcnt(30)
	v_mfma_f32_16x16x32_bf16 v[2:5], v[160:163], v[164:167], v[2:5]
	global_load_dwordx4 v[160:163], v[16:17], off offset:1984
	global_load_dwordx4 v[164:167], v[12:13], off offset:1472
	s_waitcnt vmcnt(30)
	v_mfma_f32_16x16x32_bf16 v[2:5], v[40:43], v[44:47], v[2:5]
	global_load_dwordx4 v[40:43], v[16:17], off offset:2048
	global_load_dwordx4 v[44:47], v[12:13], off offset:1536
	s_waitcnt vmcnt(30)
	v_mfma_f32_16x16x32_bf16 v[2:5], v[48:51], v[52:55], v[2:5]
	global_load_dwordx4 v[48:51], v[16:17], off offset:2112
	global_load_dwordx4 v[52:55], v[12:13], off offset:1600
	s_waitcnt vmcnt(30)
	v_mfma_f32_16x16x32_bf16 v[2:5], v[56:59], v[60:63], v[2:5]
	global_load_dwordx4 v[56:59], v[16:17], off offset:2176
	global_load_dwordx4 v[60:63], v[12:13], off offset:1664
	s_waitcnt vmcnt(30)
;     ...
;                     for (int s = 0; s < DM / 32; ++s) acc = __builtin_amdgcn_mfma_f32_16x16x32_bf16(*(const att::bf16x8*)(pa + 32 * s), *(const att::bf16x8*)(pb + 32 * s), acc, 0, 0, 0);
	v_mfma_f32_16x16x32_bf16 v[2:5], v[64:67], v[68:71], v[2:5]
	global_load_dwordx4 v[64:67], v[16:17], off offset:2240
	global_load_dwordx4 v[68:71], v[12:13], off offset:1728
	s_waitcnt vmcnt(30)
	v_mfma_f32_16x16x32_bf16 v[2:5], v[72:75], v[76:79], v[2:5]
	global_load_dwordx4 v[72:75], v[16:17], off offset:2304
	global_load_dwordx4 v[76:79], v[12:13], off offset:1792
	s_waitcnt vmcnt(30)
	v_mfma_f32_16x16x32_bf16 v[2:5], v[80:83], v[84:87], v[2:5]
	global_load_dwordx4 v[80:83], v[16:17], off offset:2368
	global_load_dwordx4 v[84:87], v[12:13], off offset:1856
	s_waitcnt vmcnt(30)
	v_mfma_f32_16x16x32_bf16 v[2:5], v[88:91], v[92:95], v[2:5]
	global_load_dwordx4 v[88:91], v[16:17], off offset:2432
	global_load_dwordx4 v[92:95], v[12:13], off offset:1920
	s_waitcnt vmcnt(30)
	v_mfma_f32_16x16x32_bf16 v[2:5], v[96:99], v[100:103], v[2:5]
	global_load_dwordx4 v[96:99], v[16:17], off offset:2496
	global_load_dwordx4 v[100:103], v[12:13], off offset:1984
	s_waitcnt vmcnt(30)
	v_mfma_f32_16x16x32_bf16 v[2:5], v[104:107], v[108:111], v[2:5]
	global_load_dwordx4 v[104:107], v[16:17], off offset:2560
	global_load_dwordx4 v[108:111], v[12:13], off offset:2048
	s_waitcnt vmcnt(30)
	v_mfma_f32_16x16x32_bf16 v[2:5], v[112:115], v[116:119], v[2:5]
	global_load_dwordx4 v[112:115], v[16:17], off offset:2624
	global_load_dwordx4 v[116:119], v[12:13], off offset:2112
	s_waitcnt vmcnt(30)
	v_mfma_f32_16x16x32_bf16 v[2:5], v[120:123], v[124:127], v[2:5]
	global_load_dwordx4 v[120:123], v[16:17], off offset:2688
	global_load_dwordx4 v[124:127], v[12:13], off offset:2176
	s_waitcnt vmcnt(30)
	v_mfma_f32_16x16x32_bf16 v[2:5], v[128:131], v[132:135], v[2:5]
	global_load_dwordx4 v[128:131], v[16:17], off offset:2752
	global_load_dwordx4 v[132:135], v[12:13], off offset:2240
	s_waitcnt vmcnt(30)
	v_mfma_f32_16x16x32_bf16 v[2:5], v[136:139], v[140:143], v[2:5]
	global_load_dwordx4 v[136:139], v[16:17], off offset:2816
	global_load_dwordx4 v[140:143], v[12:13], off offset:2304
	s_waitcnt vmcnt(30)
	v_mfma_f32_16x16x32_bf16 v[2:5], v[144:147], v[148:151], v[2:5]
	global_load_dwordx4 v[144:147], v[16:17], off offset:2880
	global_load_dwordx4 v[148:151], v[12:13], off offset:2368
	s_waitcnt vmcnt(30)
	v_mfma_f32_16x16x32_bf16 v[2:5], v[152:155], v[156:159], v[2:5]
	global_load_dwordx4 v[152:155], v[16:17], off offset:2944
	global_load_dwordx4 v[156:159], v[12:13], off offset:2432
	s_waitcnt vmcnt(30)
	v_mfma_f32_16x16x32_bf16 v[2:5], v[160:163], v[164:167], v[2:5]
	global_load_dwordx4 v[160:163], v[16:17], off offset:3008
	global_load_dwordx4 v[164:167], v[12:13], off offset:2496
	s_waitcnt vmcnt(30)
	v_mfma_f32_16x16x32_bf16 v[2:5], v[40:43], v[44:47], v[2:5]
	global_load_dwordx4 v[40:43], v[16:17], off offset:3072
	global_load_dwordx4 v[44:47], v[12:13], off offset:2560
	s_waitcnt vmcnt(30)
	v_mfma_f32_16x16x32_bf16 v[2:5], v[48:51], v[52:55], v[2:5]
	global_load_dwordx4 v[48:51], v[16:17], off offset:3136
	global_load_dwordx4 v[52:55], v[12:13], off offset:2624
	s_waitcnt vmcnt(30)
	v_mfma_f32_16x16x32_bf16 v[2:5], v[56:59], v[60:63], v[2:5]
	global_load_dwordx4 v[56:59], v[16:17], off offset:3200
	global_load_dwordx4 v[60:63], v[12:13], off offset:2688
	s_waitcnt vmcnt(30)
	v_mfma_f32_16x16x32_bf16 v[2:5], v[64:67], v[68:71], v[2:5]
	global_load_dwordx4 v[64:67], v[16:17], off offset:3264
	global_load_dwordx4 v[68:71], v[12:13], off offset:2752
	s_waitcnt vmcnt(30)
	v_mfma_f32_16x16x32_bf16 v[2:5], v[72:75], v[76:79], v[2:5]
	global_load_dwordx4 v[72:75], v[16:17], off offset:3328
	global_load_dwordx4 v[76:79], v[12:13], off offset:2816
	s_waitcnt vmcnt(30)
	v_mfma_f32_16x16x32_bf16 v[2:5], v[80:83], v[84:87], v[2:5]
	global_load_dwordx4 v[80:83], v[16:17], off offset:3392
	global_load_dwordx4 v[84:87], v[12:13], off offset:2880
	s_waitcnt vmcnt(30)
	v_mfma_f32_16x16x32_bf16 v[2:5], v[88:91], v[92:95], v[2:5]
	global_load_dwordx4 v[88:91], v[16:17], off offset:3456
	global_load_dwordx4 v[92:95], v[12:13], off offset:2944
	s_waitcnt vmcnt(30)
	v_mfma_f32_16x16x32_bf16 v[2:5], v[96:99], v[100:103], v[2:5]
	global_load_dwordx4 v[96:99], v[16:17], off offset:3520
	global_load_dwordx4 v[100:103], v[12:13], off offset:3008
	s_waitcnt vmcnt(30)
	v_mfma_f32_16x16x32_bf16 v[2:5], v[104:107], v[108:111], v[2:5]
	global_load_dwordx4 v[104:107], v[16:17], off offset:3584
	global_load_dwordx4 v[108:111], v[12:13], off offset:3072
	s_waitcnt vmcnt(30)
	v_mfma_f32_16x16x32_bf16 v[2:5], v[112:115], v[116:119], v[2:5]
	global_load_dwordx4 v[112:115], v[16:17], off offset:3648
	global_load_dwordx4 v[116:119], v[12:13], off offset:3136
	s_waitcnt vmcnt(30)
	v_mfma_f32_16x16x32_bf16 v[2:5], v[120:123], v[124:127], v[2:5]
	global_load_dwordx4 v[120:123], v[16:17], off offset:3712
	global_load_dwordx4 v[124:127], v[12:13], off offset:3200
	s_waitcnt vmcnt(30)
	v_mfma_f32_16x16x32_bf16 v[2:5], v[128:131], v[132:135], v[2:5]
	global_load_dwordx4 v[128:131], v[16:17], off offset:3776
	global_load_dwordx4 v[132:135], v[12:13], off offset:3264
	s_waitcnt vmcnt(30)
	v_mfma_f32_16x16x32_bf16 v[2:5], v[136:139], v[140:143], v[2:5]
	global_load_dwordx4 v[136:139], v[16:17], off offset:3840
	global_load_dwordx4 v[140:143], v[12:13], off offset:3328
	s_waitcnt vmcnt(30)
	v_mfma_f32_16x16x32_bf16 v[2:5], v[144:147], v[148:151], v[2:5]
	global_load_dwordx4 v[144:147], v[16:17], off offset:3904
	global_load_dwordx4 v[148:151], v[12:13], off offset:3392
	s_waitcnt vmcnt(30)
	v_mfma_f32_16x16x32_bf16 v[2:5], v[152:155], v[156:159], v[2:5]
	global_load_dwordx4 v[152:155], v[16:17], off offset:3968
	global_load_dwordx4 v[156:159], v[12:13], off offset:3456
	s_waitcnt vmcnt(30)
;     ...
;                     for (int s = 0; s < DM / 32; ++s) acc = __builtin_amdgcn_mfma_f32_16x16x32_bf16(*(const att::bf16x8*)(pa + 32 * s), *(const att::bf16x8*)(pb + 32 * s), acc, 0, 0, 0);
;                     if ((lane & 15) < 8) {
	v_mfma_f32_16x16x32_bf16 v[2:5], v[160:163], v[164:167], v[2:5]
	global_load_dwordx4 v[160:163], v[16:17], off offset:4032
	global_load_dwordx4 v[164:167], v[12:13], off offset:3520
	s_waitcnt vmcnt(30)
	v_mfma_f32_16x16x32_bf16 v[2:5], v[40:43], v[44:47], v[2:5]
	s_waitcnt vmcnt(28)
	v_mfma_f32_16x16x32_bf16 v[2:5], v[48:51], v[52:55], v[2:5]
	s_waitcnt vmcnt(26)
	v_mfma_f32_16x16x32_bf16 v[2:5], v[56:59], v[60:63], v[2:5]
	s_waitcnt vmcnt(24)
	v_mfma_f32_16x16x32_bf16 v[2:5], v[64:67], v[68:71], v[2:5]
	s_waitcnt vmcnt(22)
	v_mfma_f32_16x16x32_bf16 v[2:5], v[72:75], v[76:79], v[2:5]
	s_waitcnt vmcnt(20)
	v_mfma_f32_16x16x32_bf16 v[2:5], v[80:83], v[84:87], v[2:5]
	s_waitcnt vmcnt(18)
	v_mfma_f32_16x16x32_bf16 v[2:5], v[88:91], v[92:95], v[2:5]
	s_waitcnt vmcnt(16)
	v_mfma_f32_16x16x32_bf16 v[2:5], v[96:99], v[100:103], v[2:5]
	s_waitcnt vmcnt(14)
	v_mfma_f32_16x16x32_bf16 v[2:5], v[104:107], v[108:111], v[2:5]
	s_waitcnt vmcnt(12)
	v_mfma_f32_16x16x32_bf16 v[2:5], v[112:115], v[116:119], v[2:5]
	s_waitcnt vmcnt(10)
	v_mfma_f32_16x16x32_bf16 v[2:5], v[120:123], v[124:127], v[2:5]
	s_waitcnt vmcnt(8)
	v_mfma_f32_16x16x32_bf16 v[2:5], v[128:131], v[132:135], v[2:5]
	s_waitcnt vmcnt(6)
	v_mfma_f32_16x16x32_bf16 v[2:5], v[136:139], v[140:143], v[2:5]
	s_waitcnt vmcnt(4)
	v_mfma_f32_16x16x32_bf16 v[2:5], v[144:147], v[148:151], v[2:5]
	s_waitcnt vmcnt(2)
	v_mfma_f32_16x16x32_bf16 v[2:5], v[152:155], v[156:159], v[2:5]
	s_waitcnt vmcnt(0)
	v_mfma_f32_16x16x32_bf16 v[2:5], v[160:163], v[164:167], v[2:5]
	s_and_saveexec_b64 s[0:1], s[2:3]
	s_cbranch_execz .LBB0_524
;     ...
;                     if ((lane & 15) < 8) {
; #pragma unroll
;                         for (int i = 0; i < 4; ++i) { const int row = grp * 16 + 4 * (lane >> 4) + i;
;                             const float r = __builtin_amdgcn_rsqf(pg8::sum_parts<8>(ssqh + (size_t)row * 32) * (1.0f / 2048.0f) + 1e-6f);
;                             WIDX[(size_t)row * 8 + (lane & 15)] = acc[i] * r; }
;                     }
	v_lshl_or_b32 v14, s4, 4, v20
	v_ashrrev_i32_e32 v15, 31, v14
	v_lshlrev_b64 v[16:17], 7, v[14:15]
	v_lshl_add_u64 v[34:35], s[22:23], 0, v[16:17]
	global_load_dwordx4 v[40:43], v[34:35], off
	global_load_dwordx4 v[44:47], v[34:35], off offset:16
	global_load_dwordx4 v[48:51], v[34:35], off offset:32
	global_load_dwordx4 v[52:55], v[34:35], off offset:48
	global_load_dwordx4 v[56:59], v[34:35], off offset:64
	global_load_dwordx4 v[60:63], v[34:35], off offset:80
	global_load_dwordx4 v[64:67], v[34:35], off offset:96
	global_load_dwordx4 v[68:71], v[34:35], off offset:112
	global_load_dwordx4 v[72:75], v[34:35], off offset:128
	global_load_dwordx4 v[76:79], v[34:35], off offset:144
	global_load_dwordx4 v[80:83], v[34:35], off offset:160
	global_load_dwordx4 v[84:87], v[34:35], off offset:176
	global_load_dwordx4 v[88:91], v[34:35], off offset:192
	global_load_dwordx4 v[92:95], v[34:35], off offset:208
	global_load_dwordx4 v[96:99], v[34:35], off offset:224
	global_load_dwordx4 v[100:103], v[34:35], off offset:240
	global_load_dwordx4 v[104:107], v[34:35], off offset:256
	global_load_dwordx4 v[108:111], v[34:35], off offset:272
	global_load_dwordx4 v[112:115], v[34:35], off offset:288
	global_load_dwordx4 v[116:119], v[34:35], off offset:304
	global_load_dwordx4 v[120:123], v[34:35], off offset:320
	global_load_dwordx4 v[124:127], v[34:35], off offset:336
	global_load_dwordx4 v[128:131], v[34:35], off offset:352
	global_load_dwordx4 v[132:135], v[34:35], off offset:368
	global_load_dwordx4 v[136:139], v[34:35], off offset:384
	global_load_dwordx4 v[140:143], v[34:35], off offset:400
	global_load_dwordx4 v[144:147], v[34:35], off offset:416
	global_load_dwordx4 v[148:151], v[34:35], off offset:432
	global_load_dwordx4 v[152:155], v[34:35], off offset:448
	global_load_dwordx4 v[156:159], v[34:35], off offset:464
	global_load_dwordx4 v[160:163], v[34:35], off offset:480
	global_load_dwordx4 v[164:167], v[34:35], off offset:496
	v_lshlrev_b64 v[16:17], 5, v[14:15]
	v_lshl_add_u64 v[16:17], v[6:7], 0, v[16:17]
	s_waitcnt vmcnt(24)
	v_pk_add_f32 v[28:29], v[42:43], v[46:47]
	v_pk_add_f32 v[26:27], v[40:41], v[44:45]
	v_pk_add_f32 v[28:29], v[28:29], v[50:51]
	v_pk_add_f32 v[26:27], v[26:27], v[48:49]
	v_pk_add_f32 v[28:29], v[28:29], v[54:55]
	v_pk_add_f32 v[26:27], v[26:27], v[52:53]
	v_pk_add_f32 v[28:29], v[28:29], v[58:59]
	v_pk_add_f32 v[26:27], v[26:27], v[56:57]
	v_pk_add_f32 v[28:29], v[28:29], v[62:63]
	v_pk_add_f32 v[26:27], v[26:27], v[60:61]
	v_pk_add_f32 v[28:29], v[28:29], v[66:67]
	v_pk_add_f32 v[26:27], v[26:27], v[64:65]
	v_pk_add_f32 v[28:29], v[28:29], v[70:71]
	v_pk_add_f32 v[26:27], v[26:27], v[68:69]
	v_add_f32_e32 v11, v28, v29
	v_add_f32_e32 v0, v26, v27
	v_add_f32_e32 v0, v0, v11
	v_fmamk_f32 v0, v0, 0x3a000000, v204
	v_rsq_f32_e32 v0, v0
	s_nop 0
	v_mul_f32_e32 v30, v2, v0
	s_waitcnt vmcnt(16)
	v_pk_add_f32 v[28:29], v[74:75], v[78:79]
	v_pk_add_f32 v[26:27], v[72:73], v[76:77]
	v_pk_add_f32 v[28:29], v[28:29], v[82:83]
	v_pk_add_f32 v[26:27], v[26:27], v[80:81]
	v_pk_add_f32 v[28:29], v[28:29], v[86:87]
	v_pk_add_f32 v[26:27], v[26:27], v[84:85]
	v_pk_add_f32 v[28:29], v[28:29], v[90:91]
	v_pk_add_f32 v[26:27], v[26:27], v[88:89]
	v_pk_add_f32 v[28:29], v[28:29], v[94:95]
	v_pk_add_f32 v[26:27], v[26:27], v[92:93]
	v_pk_add_f32 v[28:29], v[28:29], v[98:99]
	v_pk_add_f32 v[26:27], v[26:27], v[96:97]
	v_pk_add_f32 v[28:29], v[28:29], v[102:103]
	v_pk_add_f32 v[26:27], v[26:27], v[100:101]
	v_add_f32_e32 v11, v28, v29
	v_add_f32_e32 v0, v26, v27
	v_add_f32_e32 v0, v0, v11
	v_fmamk_f32 v0, v0, 0x3a000000, v204
	v_rsq_f32_e32 v0, v0
	s_nop 0
	v_mul_f32_e32 v31, v3, v0
	s_waitcnt vmcnt(8)
	v_pk_add_f32 v[28:29], v[106:107], v[110:111]
	v_pk_add_f32 v[26:27], v[104:105], v[108:109]
	v_pk_add_f32 v[28:29], v[28:29], v[114:115]
	v_pk_add_f32 v[26:27], v[26:27], v[112:113]
	v_pk_add_f32 v[28:29], v[28:29], v[118:119]
	v_pk_add_f32 v[26:27], v[26:27], v[116:117]
	v_pk_add_f32 v[28:29], v[28:29], v[122:123]
	v_pk_add_f32 v[26:27], v[26:27], v[120:121]
	v_pk_add_f32 v[28:29], v[28:29], v[126:127]
	v_pk_add_f32 v[26:27], v[26:27], v[124:125]
	v_pk_add_f32 v[28:29], v[28:29], v[130:131]
	v_pk_add_f32 v[26:27], v[26:27], v[128:129]
	v_pk_add_f32 v[28:29], v[28:29], v[134:135]
	v_pk_add_f32 v[26:27], v[26:27], v[132:133]
	v_add_f32_e32 v11, v28, v29
	v_add_f32_e32 v0, v26, v27
	v_add_f32_e32 v0, v0, v11
	v_fmamk_f32 v0, v0, 0x3a000000, v204
	v_rsq_f32_e32 v0, v0
	s_nop 0
	v_mul_f32_e32 v32, v4, v0
	s_waitcnt vmcnt(0)
	v_pk_add_f32 v[28:29], v[138:139], v[142:143]
	v_pk_add_f32 v[26:27], v[136:137], v[140:141]
	v_pk_add_f32 v[28:29], v[28:29], v[146:147]
	v_pk_add_f32 v[26:27], v[26:27], v[144:145]
	v_pk_add_f32 v[28:29], v[28:29], v[150:151]
	v_pk_add_f32 v[26:27], v[26:27], v[148:149]
	v_pk_add_f32 v[28:29], v[28:29], v[154:155]
	v_pk_add_f32 v[26:27], v[26:27], v[152:153]
	v_pk_add_f32 v[28:29], v[28:29], v[158:159]
	v_pk_add_f32 v[26:27], v[26:27], v[156:157]
	v_pk_add_f32 v[28:29], v[28:29], v[162:163]
	v_pk_add_f32 v[26:27], v[26:27], v[160:161]
	v_pk_add_f32 v[28:29], v[28:29], v[166:167]
	v_pk_add_f32 v[26:27], v[26:27], v[164:165]
	v_add_f32_e32 v11, v28, v29
	v_add_f32_e32 v0, v26, v27
	v_add_f32_e32 v0, v0, v11
	v_fmamk_f32 v0, v0, 0x3a000000, v204
	v_rsq_f32_e32 v0, v0
	s_nop 0
	v_mul_f32_e32 v33, v5, v0
	global_store_dword v[16:17], v30, off
	global_store_dword v[16:17], v31, off offset:32
	global_store_dword v[16:17], v32, off offset:64
	global_store_dword v[16:17], v33, off offset:96
	s_branch .LBB0_524
